# v12 + hyena filter-table loads de-serialised (all chunk loads issued before the first wait)
# speedup vs baseline: 1.0009x; 1.0009x over previous
; DI void hy_load_table(const u16* __restrict__ tbg, u16* TbE, u16* TbO, int tid) {
; #pragma unroll
;   for (int i = 0; i < 4; ++i) {
;     const int q = tid + NT * i;
;     const uint4 v = *(const uint4*)(tbg + 8 * q);
;     const unsigned nxt = (q < 2047) ? (unsigned)tbg[8 * q + 8] : 0u;
;     *(uint4*)(TbE + 8 * q) = v;
;     uint4 o;
;     o.x = (v.x >> 16) | (v.y << 16);
;     o.y = (v.y >> 16) | (v.z << 16);
;     o.z = (v.z >> 16) | (v.w << 16);
;     o.w = (v.w >> 16) | (nxt << 16);
;     *(uint4*)(TbO + 8 * q) = o;
;   }
; }
; DI void hyena_item(const P& p, int l, int c, char* smem) {
;     ...
;   if (tid < 68) ((unsigned*)Zrow)[tid] = 0u;
;   hy_load_table(tbg, TbE, TbO, tid);
;   const float* cw = p.conv_w + (size_t)l * 3 * 1536;
;   const float* cbias = p.conv_b + (size_t)l * 1536;
;   {
;     const float w0 = cw[c], w1 = cw[1536 + c], w2 = cw[3072 + c], bs = cbias[c];
; #pragma unroll
;     for (int i = 0; i < 4; ++i) {
;       const int q = tid + NT * i;
;       const int bt = q >> 10, t8 = (q & 1023) * 8;
;       const u16* row = p.hyT + (size_t)c * HYP + bt * SEQ;
;       float o0[4], o1[4];
;       sconv4(row, t8, w0, w1, w2, bs, o0);
.LBB0_407:
	s_or_b64 exec, exec, s[8:9]
	s_movk_i32 s8, 0x44
	v_cmp_gt_i32_e32 vcc, s8, v20
	s_and_saveexec_b64 s[8:9], vcc
	v_lshl_add_u32 v0, v20, 2, 0
	v_add_u32_e32 v0, 0x18880, v0
	ds_write_b32 v0, v189
	s_or_b64 exec, exec, s[8:9]
	s_lshl_b64 s[8:9], s[72:73], 15
	s_add_u32 s76, s50, s8
	v_lshlrev_b32_e32 v190, 3, v20
	s_addc_u32 s77, s51, s9
	v_ashrrev_i32_e32 v191, 31, v190
	v_lshl_add_u32 v221, v190, 1, 0
	v_add_u32_e32 v192, 0x1000, v190
	v_ashrrev_i32_e32 v193, 31, v192
	v_add_u32_e32 v194, 0x2000, v190
	v_ashrrev_i32_e32 v195, 31, v194
	v_add_u32_e32 v196, 0x3000, v190
	v_ashrrev_i32_e32 v197, 31, v196
	s_movk_i32 s8, 0x7ff
	v_cmp_gt_i32_e64 s[8:9], s8, v20
	s_movk_i32 s10, 0x5ff
	v_cmp_gt_i32_e64 s[10:11], s10, v20
	s_movk_i32 s12, 0x3ff
	v_cmp_gt_i32_e64 s[12:13], s12, v20
	s_movk_i32 s14, 0x1ff
	v_cmp_gt_i32_e64 s[14:15], s14, v20
	s_waitcnt lgkmcnt(0)
	v_add_u32_e32 v244, 0x2000, v221
	v_add_u32_e32 v245, 0x4000, v221
	v_add_u32_e32 v246, 0x6000, v221
	global_load_dwordx4 v[224:227], v221, s[76:77]
	global_load_dwordx4 v[228:231], v244, s[76:77]
	global_load_dwordx4 v[232:235], v245, s[76:77]
	global_load_dwordx4 v[236:239], v246, s[76:77]
	global_load_ushort v240, v221, s[76:77] offset:16
	global_load_ushort v241, v244, s[76:77] offset:16
	global_load_ushort v242, v245, s[76:77] offset:16
	global_load_ushort v243, v246, s[76:77] offset:16
	s_lshl_b64 s[78:79], s[72:73], 2
	s_add_u32 s74, s28, s78
	s_addc_u32 s75, s29, s79
	s_or_b32 s56, s72, 0x600
	s_lshl_b64 s[80:81], s[56:57], 2
	s_add_u32 s80, s28, s80
	s_addc_u32 s81, s29, s81
	s_add_u32 s82, s74, 0x3000
	s_addc_u32 s83, s75, 0
	v_readlane_b32 s73, v248, 28
	s_nop 1
	s_add_u32 s84, s73, s78
	v_readlane_b32 s73, v248, 29
	s_nop 1
	s_waitcnt vmcnt(7)
	ds_write_b128 v221, v[224:227] offset:0
	s_waitcnt vmcnt(6)
	ds_write_b128 v221, v[228:231] offset:8192
	s_waitcnt vmcnt(5)
	ds_write_b128 v221, v[232:235] offset:16384
	s_waitcnt vmcnt(4)
	ds_write_b128 v221, v[236:239] offset:24576
	s_waitcnt vmcnt(0)
	v_cndmask_b32_e64 v243, 0, v243, s[14:15]
	v_alignbit_b32 v0, v225, v224, 16
	v_alignbit_b32 v1, v226, v225, 16
	v_alignbit_b32 v2, v227, v226, 16
	v_alignbit_b32 v3, v240, v227, 16
	ds_write_b128 v221, v[0:3] offset:32832
	v_alignbit_b32 v0, v229, v228, 16
	v_alignbit_b32 v1, v230, v229, 16
	v_alignbit_b32 v2, v231, v230, 16
	v_alignbit_b32 v3, v241, v231, 16
	ds_write_b128 v221, v[0:3] offset:41024
	v_alignbit_b32 v0, v233, v232, 16
	v_alignbit_b32 v1, v234, v233, 16
	v_alignbit_b32 v2, v235, v234, 16
	v_alignbit_b32 v3, v242, v235, 16
	ds_write_b128 v221, v[0:3] offset:49216
	v_alignbit_b32 v0, v237, v236, 16
	v_alignbit_b32 v1, v238, v237, 16
	v_alignbit_b32 v2, v239, v238, 16
	v_alignbit_b32 v3, v243, v239, 16
	ds_write_b128 v221, v[0:3] offset:57408
	s_addc_u32 s85, s73, s79
	s_mul_i32 s96, s72, 0x8080
	v_ashrrev_i32_e32 v1, 10, v20
	s_mul_hi_u32 s73, s72, 0x8080
	s_add_u32 s86, s36, s96
	v_lshlrev_b32_e32 v6, 13, v1
	v_and_b32_e32 v5, 0x1ff8, v190
	s_addc_u32 s87, s37, s73
	v_ashrrev_i32_e32 v7, 31, v6
	v_lshl_add_u64 v[6:7], v[6:7], 1, s[86:87]
	v_lshlrev_b32_e32 v188, 1, v5
	v_lshl_add_u64 v[10:11], v[6:7], 0, v[188:189]
	global_load_dword v3, v189, s[74:75]
	global_load_dword v2, v189, s[80:81]
	global_load_dword v4, v189, s[84:85]
	global_load_dword v0, v205, s[74:75]
	global_load_dwordx2 v[6:7], v[10:11], off
	v_cmp_ne_u32_e32 vcc, 0, v5
	v_mov_b32_e32 v9, 0
	v_mov_b32_e32 v15, 0
	s_and_saveexec_b64 s[78:79], vcc
	s_cbranch_execz .LBB0_419
	global_load_ushort v8, v[10:11], off offset:-2
	s_waitcnt vmcnt(0)
	v_lshlrev_b32_e32 v15, 16, v8

; DI void hy_load_table(const u16* __restrict__ tbg, u16* TbE, u16* TbO, int tid) {
; #pragma unroll
;   for (int i = 0; i < 4; ++i) {
;     const int q = tid + NT * i;
;     const uint4 v = *(const uint4*)(tbg + 8 * q);
;     const unsigned nxt = (q < 2047) ? (unsigned)tbg[8 * q + 8] : 0u;
;     *(uint4*)(TbE + 8 * q) = v;
;     uint4 o;
;     o.x = (v.x >> 16) | (v.y << 16);
;     o.y = (v.y >> 16) | (v.z << 16);
;     o.z = (v.z >> 16) | (v.w << 16);
;     o.w = (v.w >> 16) | (nxt << 16);
;     *(uint4*)(TbO + 8 * q) = o;
;   }
; }
; DI void hyena_item(const P& p, int l, int c, char* smem) {
;     ...
;   hy_load_table(tbg + (size_t)512 * 16384, TbE, TbO, tid);
;   __syncthreads();
;   if (cwv) hy_conv(acc, abase, U, Zrow, a0, li, g);
.LBB0_447:
	s_or_b64 exec, exec, s[78:79]
	s_add_u32 s76, s76, 0x1000000
	s_addc_u32 s77, s77, 0
	v_add_u32_e32 v52, 0x2000, v221
	v_add_u32_e32 v53, 0x4000, v221
	v_add_u32_e32 v54, 0x6000, v221
	global_load_dwordx4 v[32:35], v221, s[76:77]
	global_load_dwordx4 v[36:39], v52, s[76:77]
	global_load_dwordx4 v[40:43], v53, s[76:77]
	global_load_dwordx4 v[44:47], v54, s[76:77]
	global_load_ushort v48, v221, s[76:77] offset:16
	global_load_ushort v49, v52, s[76:77] offset:16
	global_load_ushort v50, v53, s[76:77] offset:16
	global_load_ushort v51, v54, s[76:77] offset:16
	s_waitcnt vmcnt(7)
	ds_write_b128 v221, v[32:35] offset:0
	s_waitcnt vmcnt(6)
	ds_write_b128 v221, v[36:39] offset:8192
	s_waitcnt vmcnt(5)
	ds_write_b128 v221, v[40:43] offset:16384
	s_waitcnt vmcnt(4)
	ds_write_b128 v221, v[44:47] offset:24576
	s_waitcnt vmcnt(0)
	v_cndmask_b32_e64 v51, 0, v51, s[14:15]
	v_alignbit_b32 v56, v33, v32, 16
	v_alignbit_b32 v57, v34, v33, 16
	v_alignbit_b32 v58, v35, v34, 16
	v_alignbit_b32 v59, v48, v35, 16
	ds_write_b128 v221, v[56:59] offset:32832
	v_alignbit_b32 v56, v37, v36, 16
	v_alignbit_b32 v57, v38, v37, 16
	v_alignbit_b32 v58, v39, v38, 16
	v_alignbit_b32 v59, v49, v39, 16
	ds_write_b128 v221, v[56:59] offset:41024
	v_alignbit_b32 v56, v41, v40, 16
	v_alignbit_b32 v57, v42, v41, 16
	v_alignbit_b32 v58, v43, v42, 16
	v_alignbit_b32 v59, v50, v43, 16
	ds_write_b128 v221, v[56:59] offset:49216
	v_alignbit_b32 v56, v45, v44, 16
	v_alignbit_b32 v57, v46, v45, 16
	v_alignbit_b32 v58, v47, v46, 16
	v_alignbit_b32 v59, v51, v47, 16
	ds_write_b128 v221, v[56:59] offset:57408
	s_mov_b64 s[10:11], 0
	s_mov_b64 s[8:9], 0
	s_waitcnt lgkmcnt(0)
	s_barrier
	s_and_saveexec_b64 s[12:13], s[6:7]
	s_cbranch_execz .LBB0_463
	s_movk_i32 s6, 0xff00
	v_mad_i32_i24 v0, v228, s6, v225
	ds_read2_b32 v[152:153], v0 offset0:56 offset1:57
	ds_read2_b32 v[154:155], v0 offset0:58 offset1:59
	ds_read2_b32 v[148:149], v0 offset0:48 offset1:49
	ds_read2_b32 v[150:151], v0 offset0:50 offset1:51
	ds_read2_b32 v[140:141], v0 offset0:40 offset1:41
	ds_read2_b32 v[142:143], v0 offset0:42 offset1:43
	ds_read2_b32 v[136:137], v0 offset0:32 offset1:33
	ds_read2_b32 v[138:139], v0 offset0:34 offset1:35
	ds_read2_b32 v[128:129], v0 offset0:24 offset1:25
	ds_read2_b32 v[130:131], v0 offset0:26 offset1:27
	ds_read2_b32 v[132:133], v0 offset0:16 offset1:17
	ds_read2_b32 v[134:135], v0 offset0:18 offset1:19
	ds_read2_b32 v[120:121], v0 offset0:8 offset1:9
	ds_read2_b32 v[122:123], v0 offset0:10 offset1:11
	ds_read2_b32 v[124:125], v0 offset1:1
	ds_read2_b32 v[126:127], v0 offset0:2 offset1:3
	v_subrev_u32_e32 v1, 32, v0
	v_subrev_u32_e32 v2, 24, v0
	v_subrev_u32_e32 v3, 64, v0
	v_subrev_u32_e32 v4, 56, v0
	ds_read2_b32 v[100:101], v1 offset1:1
	ds_read2_b32 v[102:103], v2 offset1:1
	ds_read2_b32 v[92:93], v3 offset1:1
	ds_read2_b32 v[94:95], v4 offset1:1
	v_add_u32_e32 v1, 0xffffffa0, v0
	v_add_u32_e32 v2, 0xffffffa8, v0
	v_add_u32_e32 v3, 0xffffff80, v0
	v_add_u32_e32 v4, 0xffffff88, v0
	ds_read2_b32 v[96:97], v1 offset1:1
	ds_read2_b32 v[98:99], v2 offset1:1
	ds_read2_b32 v[104:105], v3 offset1:1
	ds_read2_b32 v[106:107], v4 offset1:1
	v_add_u32_e32 v1, 0xffffff60, v0
	v_add_u32_e32 v2, 0xffffff68, v0
	v_add_u32_e32 v3, 0xffffff40, v0
	v_add_u32_e32 v0, 0xffffff48, v0
	ds_read2_b32 v[108:109], v1 offset1:1
	ds_read2_b32 v[110:111], v2 offset1:1
	ds_read2_b32 v[112:113], v3 offset1:1
	ds_read2_b32 v[114:115], v0 offset1:1
	v_add_u32_e32 v0, v229, v224
	v_sub_u32_e32 v0, v0, v228
	v_mov_b32_e32 v1, s69
	v_mad_u32_u24 v185, v0, s97, v1
	v_mov_b32_e32 v0, 0
	v_sub_u32_e32 v188, v229, v228
	s_mov_b64 s[6:7], 0
	v_mov_b32_e32 v1, v0
	v_mov_b32_e32 v2, v0
	v_mov_b32_e32 v3, v0
	v_mov_b32_e32 v4, v0
	v_mov_b32_e32 v5, v0
	v_mov_b32_e32 v6, v0
	v_mov_b32_e32 v7, v0
	v_mov_b32_e32 v8, v0
	v_mov_b32_e32 v9, v0
	v_mov_b32_e32 v10, v0
	v_mov_b32_e32 v11, v0
	v_mov_b32_e32 v12, v0
	v_mov_b32_e32 v13, v0
	v_mov_b32_e32 v14, v0
	v_mov_b32_e32 v15, v0
	v_mov_b32_e32 v16, v0
	v_mov_b32_e32 v17, v0
	v_mov_b32_e32 v18, v0
	v_mov_b32_e32 v19, v0
	v_mov_b32_e32 v20, v0
	v_mov_b32_e32 v21, v0
	v_mov_b32_e32 v22, v0
	v_mov_b32_e32 v23, v0
	v_mov_b32_e32 v24, v0
	v_mov_b32_e32 v25, v0
	v_mov_b32_e32 v26, v0
	v_mov_b32_e32 v27, v0
	v_mov_b32_e32 v28, v0
	v_mov_b32_e32 v29, v0
	v_mov_b32_e32 v30, v0
	v_mov_b32_e32 v31, v0
	v_mov_b32_e32 v32, v0
	v_mov_b32_e32 v33, v0
	v_mov_b32_e32 v34, v0
	v_mov_b32_e32 v35, v0
	v_mov_b32_e32 v36, v0
	v_mov_b32_e32 v37, v0
	v_mov_b32_e32 v38, v0
	v_mov_b32_e32 v39, v0
	v_mov_b32_e32 v40, v0
	v_mov_b32_e32 v41, v0
	v_mov_b32_e32 v42, v0
	v_mov_b32_e32 v43, v0
	v_mov_b32_e32 v44, v0
	v_mov_b32_e32 v45, v0
	v_mov_b32_e32 v46, v0
	v_mov_b32_e32 v47, v0
	v_mov_b32_e32 v48, v0
	v_mov_b32_e32 v49, v0
	v_mov_b32_e32 v50, v0
	v_mov_b32_e32 v51, v0
	v_mov_b32_e32 v52, v0
	v_mov_b32_e32 v53, v0
	v_mov_b32_e32 v54, v0
	v_mov_b32_e32 v55, v0
	v_mov_b32_e32 v56, v0
	v_mov_b32_e32 v57, v0
	v_mov_b32_e32 v58, v0
	v_mov_b32_e32 v59, v0
	v_mov_b32_e32 v60, v0
	v_mov_b32_e32 v61, v0
	v_mov_b32_e32 v62, v0
	v_mov_b32_e32 v63, v0
